# RWKV scan inner loop hand-rescheduled: 4 steps per iteration, dot products as packed-fma chains, immediate-offset y stores
# speedup vs baseline: 1.0429x; 1.0125x over previous
; #define LAS __attribute__((address_space(3)))
; template <int ph>
; __device__ __forceinline__ void run_phase(const Args& args, LAS unsigned char* lds, const int G, const int bx, const bool fin = true) {
;     ...
;                     const LAS float* V = VECb + buf * VB + 8 * kq; const LAS float* SCp = SCb + buf * TC * 2;
;                     LAS float* YBp = (kq == 0) ? (YBb + buf * TC * 32 + rowl) : (YBb + 2 * TC * 32 + wave * 64 + lane); const int ystr = (kq == 0) ? 32 : 0;
;                     const LAS float* Vv = VECb + buf * VB + 5 * TC * 64 + srow;
;     ...
;                     { SCAN_LOAD(a, 0)
; #pragma unroll 1
;                       for (int t = 0; t < TC; t += 2) {
;                           SCAN_LOAD(b, t + 1)
;                           __builtin_amdgcn_sched_barrier(0);
;                           SCAN_STEP(a, t)
;                           __builtin_amdgcn_sched_barrier(0);
;                           { const LAS float* pn = V + (t + 2) * 64;
;                             nkAa = *(const LAS f32x4*)(pn); nkBa = *(const LAS f32x4*)(pn + 4); wrAa = *(const LAS f32x4*)(pn + 1 * TC * 64); wrBa = *(const LAS f32x4*)(pn + 1 * TC * 64 + 4);
;                             wAa = *(const LAS f32x4*)(pn + 2 * TC * 64); wBa = *(const LAS f32x4*)(pn + 2 * TC * 64 + 4); bAa = *(const LAS f32x4*)(pn + 3 * TC * 64); bBa = *(const LAS f32x4*)(pn + 3 * TC * 64 + 4);
;                             kAa = *(const LAS f32x4*)(pn + 4 * TC * 64); kBa = *(const LAS f32x4*)(pn + 4 * TC * 64 + 4); vva = Vv[(t + 2) * 64]; sca = *(const LAS f32x2*)(SCp + 2 * (t + 2)); }
;                           __builtin_amdgcn_sched_barrier(0);
;                           SCAN_STEP(b, t + 1)
;                           __builtin_amdgcn_sched_barrier(0);
;                       } }
.LBB0_1007:
	s_and_b32 s61, s60, 1
	s_mov_b64 s[0:1], -1
	s_and_b64 vcc, exec, s[16:17]
	s_cbranch_vccz .LBB0_1011
	v_cndmask_b32_e64 v28, 0, 1, s[46:47]
	s_mul_i32 s0, s61, 0xc000
	v_lshlrev_b32_e32 v29, 8, v28
	v_mul_lo_u32 v28, v28, s57
	s_add_i32 s0, s0, 0
	v_add_u32_e32 v29, 0, v29
	v_add_u32_e32 v156, v87, v28
	v_add_u32_e32 v157, v149, v28
	v_add_u32_e32 v159, s0, v80
	v_lshl_add_u32 v28, s61, 12, v144
	v_add_u32_e32 v155, 0x18008, v29
	v_cndmask_b32_e64 v158, v145, v28, s[4:5]
	s_lshl_b32 s1, s61, 8
	s_add_i32 s1, s1, 0
	s_add_i32 s1, s1, 0x18000
	v_lshl_add_u32 v72, v154, 2, s0
	v_mov_b32_e32 v128, s1
	ds_read_b128 v[60:63], v159
	ds_read_b128 v[64:67], v159 offset:16
	ds_read_b128 v[48:51], v159 offset:8192
	ds_read_b128 v[56:59], v159 offset:8208
	ds_read_b128 v[40:43], v159 offset:16384
	ds_read_b128 v[36:39], v159 offset:16400
	ds_read_b128 v[32:35], v159 offset:24576
	ds_read_b128 v[28:31], v159 offset:24592
	ds_read_b128 v[52:55], v159 offset:32768
	ds_read_b128 v[44:47], v159 offset:32784
	ds_read_b32 v72, v72 offset:40960
	ds_read_b64 v[128:129], v128
	ds_write_b32 v158, v158
	s_mov_b32 s0, 0
	v_mov_b64_e32 v[130:131], v[24:25]
	v_mov_b64_e32 v[132:133], v[26:27]
	v_mov_b64_e32 v[134:135], v[20:21]
	v_mov_b64_e32 v[136:137], v[22:23]
.LBB0_1009:
	ds_read_b128 v[160:163], v157
	ds_read_b128 v[164:167], v157 offset:16
	ds_read_b128 v[168:171], v157 offset:8192
	ds_read_b128 v[172:175], v157 offset:8208
	ds_read_b128 v[176:179], v157 offset:16384
	ds_read_b128 v[180:183], v157 offset:16400
	ds_read_b128 v[184:187], v157 offset:24576
	ds_read_b128 v[188:191], v157 offset:24592
	ds_read_b128 v[192:195], v157 offset:32768
	ds_read_b128 v[196:199], v157 offset:32784
	ds_read_b32 v200, v156
	ds_read_b64 v[204:205], v155
	s_waitcnt lgkmcnt(13)
	v_pk_mul_f32 v[60:61], v[130:131], v[60:61]
	v_pk_mul_f32 v[48:49], v[130:131], v[48:49]
	v_pk_mul_f32 v[52:53], v[52:53], v[72:73] op_sel_hi:[1,0]
	v_pk_fma_f32 v[60:61], v[132:133], v[62:63], v[60:61]
	v_pk_fma_f32 v[48:49], v[132:133], v[50:51], v[48:49]
	v_pk_mul_f32 v[54:55], v[54:55], v[72:73] op_sel_hi:[1,0]
	v_pk_fma_f32 v[60:61], v[134:135], v[64:65], v[60:61]
	v_pk_fma_f32 v[48:49], v[134:135], v[56:57], v[48:49]
	v_pk_mul_f32 v[44:45], v[44:45], v[72:73] op_sel_hi:[1,0]
	v_pk_fma_f32 v[60:61], v[136:137], v[66:67], v[60:61]
	v_pk_fma_f32 v[48:49], v[136:137], v[58:59], v[48:49]
	v_pk_mul_f32 v[46:47], v[46:47], v[72:73] op_sel_hi:[1,0]
	v_add_f32_e32 v64, v60, v61
	v_add_f32_e32 v65, v48, v49
	v_pk_fma_f32 v[52:53], v[130:131], v[40:41], v[52:53]
	v_pk_fma_f32 v[54:55], v[132:133], v[42:43], v[54:55]
	v_add_f32_dpp v64, v64, v64 quad_perm:[1,0,3,2] row_mask:0xf bank_mask:0xf bound_ctrl:1
	v_add_f32_dpp v65, v65, v65 quad_perm:[1,0,3,2] row_mask:0xf bank_mask:0xf bound_ctrl:1
	v_pk_fma_f32 v[44:45], v[134:135], v[36:37], v[44:45]
	v_add_f32_dpp v64, v64, v64 quad_perm:[2,3,0,1] row_mask:0xf bank_mask:0xf bound_ctrl:1
	v_add_f32_dpp v65, v65, v65 quad_perm:[2,3,0,1] row_mask:0xf bank_mask:0xf bound_ctrl:1
	v_pk_fma_f32 v[46:47], v[136:137], v[38:39], v[46:47]
	v_add_f32_dpp v64, v64, v64 row_half_mirror row_mask:0xf bank_mask:0xf bound_ctrl:1
	v_add_f32_dpp v65, v65, v65 row_half_mirror row_mask:0xf bank_mask:0xf bound_ctrl:1
	v_pk_fma_f32 v[130:131], v[32:33], v[64:65], v[52:53] op_sel_hi:[1,0,1]
	v_pk_fma_f32 v[132:133], v[34:35], v[64:65], v[54:55] op_sel_hi:[1,0,1]
	v_pk_fma_f32 v[134:135], v[28:29], v[64:65], v[44:45] op_sel_hi:[1,0,1]
	v_pk_fma_f32 v[136:137], v[30:31], v[64:65], v[46:47] op_sel_hi:[1,0,1]
	v_fmac_f32_e32 v65, v72, v129
	v_fmac_f32_e32 v65, v128, v64
	ds_write_b32 v158, v65
	ds_read_b128 v[60:63], v157 offset:256
	ds_read_b128 v[64:67], v157 offset:272
	ds_read_b128 v[48:51], v157 offset:8448
	ds_read_b128 v[56:59], v157 offset:8464
	ds_read_b128 v[40:43], v157 offset:16640
	ds_read_b128 v[36:39], v157 offset:16656
	ds_read_b128 v[32:35], v157 offset:24832
	ds_read_b128 v[28:31], v157 offset:24848
	ds_read_b128 v[52:55], v157 offset:33024
	ds_read_b128 v[44:47], v157 offset:33040
	ds_read_b32 v72, v156 offset:256
	ds_read_b64 v[128:129], v155 offset:8
	s_waitcnt lgkmcnt(13)
	v_pk_mul_f32 v[160:161], v[130:131], v[160:161]
	v_pk_mul_f32 v[168:169], v[130:131], v[168:169]
	v_pk_mul_f32 v[192:193], v[192:193], v[200:201] op_sel_hi:[1,0]
	v_pk_fma_f32 v[160:161], v[132:133], v[162:163], v[160:161]
	v_pk_fma_f32 v[168:169], v[132:133], v[170:171], v[168:169]
	v_pk_mul_f32 v[194:195], v[194:195], v[200:201] op_sel_hi:[1,0]
	v_pk_fma_f32 v[160:161], v[134:135], v[164:165], v[160:161]
	v_pk_fma_f32 v[168:169], v[134:135], v[172:173], v[168:169]
	v_pk_mul_f32 v[196:197], v[196:197], v[200:201] op_sel_hi:[1,0]
	v_pk_fma_f32 v[160:161], v[136:137], v[166:167], v[160:161]
	v_pk_fma_f32 v[168:169], v[136:137], v[174:175], v[168:169]
	v_pk_mul_f32 v[198:199], v[198:199], v[200:201] op_sel_hi:[1,0]
	v_add_f32_e32 v164, v160, v161
	v_add_f32_e32 v165, v168, v169
	v_pk_fma_f32 v[192:193], v[130:131], v[176:177], v[192:193]
	v_pk_fma_f32 v[194:195], v[132:133], v[178:179], v[194:195]
	v_add_f32_dpp v164, v164, v164 quad_perm:[1,0,3,2] row_mask:0xf bank_mask:0xf bound_ctrl:1
	v_add_f32_dpp v165, v165, v165 quad_perm:[1,0,3,2] row_mask:0xf bank_mask:0xf bound_ctrl:1
	v_pk_fma_f32 v[196:197], v[134:135], v[180:181], v[196:197]
	v_add_f32_dpp v164, v164, v164 quad_perm:[2,3,0,1] row_mask:0xf bank_mask:0xf bound_ctrl:1
	v_add_f32_dpp v165, v165, v165 quad_perm:[2,3,0,1] row_mask:0xf bank_mask:0xf bound_ctrl:1
	v_pk_fma_f32 v[198:199], v[136:137], v[182:183], v[198:199]
	v_add_f32_dpp v164, v164, v164 row_half_mirror row_mask:0xf bank_mask:0xf bound_ctrl:1
	v_add_f32_dpp v165, v165, v165 row_half_mirror row_mask:0xf bank_mask:0xf bound_ctrl:1
	v_pk_fma_f32 v[130:131], v[184:185], v[164:165], v[192:193] op_sel_hi:[1,0,1]
	v_pk_fma_f32 v[132:133], v[186:187], v[164:165], v[194:195] op_sel_hi:[1,0,1]
	v_pk_fma_f32 v[134:135], v[188:189], v[164:165], v[196:197] op_sel_hi:[1,0,1]
	v_pk_fma_f32 v[136:137], v[190:191], v[164:165], v[198:199] op_sel_hi:[1,0,1]
	v_fmac_f32_e32 v165, v200, v205
	v_fmac_f32_e32 v165, v204, v164
	ds_write_b32 v158, v165 offset:128
	ds_read_b128 v[160:163], v157 offset:512
	ds_read_b128 v[164:167], v157 offset:528
	ds_read_b128 v[168:171], v157 offset:8704
	ds_read_b128 v[172:175], v157 offset:8720
	ds_read_b128 v[176:179], v157 offset:16896
	ds_read_b128 v[180:183], v157 offset:16912
	ds_read_b128 v[184:187], v157 offset:25088
	ds_read_b128 v[188:191], v157 offset:25104
	ds_read_b128 v[192:195], v157 offset:33280
	ds_read_b128 v[196:199], v157 offset:33296
	ds_read_b32 v200, v156 offset:512
	ds_read_b64 v[204:205], v155 offset:16
	s_waitcnt lgkmcnt(13)
; #define LAS __attribute__((address_space(3)))
; template <int ph>
; __device__ __forceinline__ void run_phase(const Args& args, LAS unsigned char* lds, const int G, const int bx, const bool fin = true) {
;     ...
;                     { SCAN_LOAD(a, 0)
; #pragma unroll 1
;                       for (int t = 0; t < TC; t += 2) {
;                           SCAN_LOAD(b, t + 1)
;                           __builtin_amdgcn_sched_barrier(0);
;                           SCAN_STEP(a, t)
;                           __builtin_amdgcn_sched_barrier(0);
;                           { const LAS float* pn = V + (t + 2) * 64;
;                             nkAa = *(const LAS f32x4*)(pn); nkBa = *(const LAS f32x4*)(pn + 4); wrAa = *(const LAS f32x4*)(pn + 1 * TC * 64); wrBa = *(const LAS f32x4*)(pn + 1 * TC * 64 + 4);
;                             wAa = *(const LAS f32x4*)(pn + 2 * TC * 64); wBa = *(const LAS f32x4*)(pn + 2 * TC * 64 + 4); bAa = *(const LAS f32x4*)(pn + 3 * TC * 64); bBa = *(const LAS f32x4*)(pn + 3 * TC * 64 + 4);
;                             kAa = *(const LAS f32x4*)(pn + 4 * TC * 64); kBa = *(const LAS f32x4*)(pn + 4 * TC * 64 + 4); vva = Vv[(t + 2) * 64]; sca = *(const LAS f32x2*)(SCp + 2 * (t + 2)); }
;                           __builtin_amdgcn_sched_barrier(0);
;                           SCAN_STEP(b, t + 1)
;                           __builtin_amdgcn_sched_barrier(0);
;                       } }
	v_pk_mul_f32 v[60:61], v[130:131], v[60:61]
	v_pk_mul_f32 v[48:49], v[130:131], v[48:49]
	v_pk_mul_f32 v[52:53], v[52:53], v[72:73] op_sel_hi:[1,0]
	v_pk_fma_f32 v[60:61], v[132:133], v[62:63], v[60:61]
	v_pk_fma_f32 v[48:49], v[132:133], v[50:51], v[48:49]
	v_pk_mul_f32 v[54:55], v[54:55], v[72:73] op_sel_hi:[1,0]
	v_pk_fma_f32 v[60:61], v[134:135], v[64:65], v[60:61]
	v_pk_fma_f32 v[48:49], v[134:135], v[56:57], v[48:49]
	v_pk_mul_f32 v[44:45], v[44:45], v[72:73] op_sel_hi:[1,0]
	v_pk_fma_f32 v[60:61], v[136:137], v[66:67], v[60:61]
	v_pk_fma_f32 v[48:49], v[136:137], v[58:59], v[48:49]
	v_pk_mul_f32 v[46:47], v[46:47], v[72:73] op_sel_hi:[1,0]
	v_add_f32_e32 v64, v60, v61
	v_add_f32_e32 v65, v48, v49
	v_pk_fma_f32 v[52:53], v[130:131], v[40:41], v[52:53]
	v_pk_fma_f32 v[54:55], v[132:133], v[42:43], v[54:55]
	v_add_f32_dpp v64, v64, v64 quad_perm:[1,0,3,2] row_mask:0xf bank_mask:0xf bound_ctrl:1
	v_add_f32_dpp v65, v65, v65 quad_perm:[1,0,3,2] row_mask:0xf bank_mask:0xf bound_ctrl:1
	v_pk_fma_f32 v[44:45], v[134:135], v[36:37], v[44:45]
	v_add_f32_dpp v64, v64, v64 quad_perm:[2,3,0,1] row_mask:0xf bank_mask:0xf bound_ctrl:1
	v_add_f32_dpp v65, v65, v65 quad_perm:[2,3,0,1] row_mask:0xf bank_mask:0xf bound_ctrl:1
	v_pk_fma_f32 v[46:47], v[136:137], v[38:39], v[46:47]
	v_add_f32_dpp v64, v64, v64 row_half_mirror row_mask:0xf bank_mask:0xf bound_ctrl:1
	v_add_f32_dpp v65, v65, v65 row_half_mirror row_mask:0xf bank_mask:0xf bound_ctrl:1
	v_pk_fma_f32 v[130:131], v[32:33], v[64:65], v[52:53] op_sel_hi:[1,0,1]
	v_pk_fma_f32 v[132:133], v[34:35], v[64:65], v[54:55] op_sel_hi:[1,0,1]
	v_pk_fma_f32 v[134:135], v[28:29], v[64:65], v[44:45] op_sel_hi:[1,0,1]
	v_pk_fma_f32 v[136:137], v[30:31], v[64:65], v[46:47] op_sel_hi:[1,0,1]
	v_fmac_f32_e32 v65, v72, v129
	v_fmac_f32_e32 v65, v128, v64
	ds_write_b32 v158, v65 offset:256
	ds_read_b128 v[60:63], v157 offset:768
	ds_read_b128 v[64:67], v157 offset:784
	ds_read_b128 v[48:51], v157 offset:8960
	ds_read_b128 v[56:59], v157 offset:8976
	ds_read_b128 v[40:43], v157 offset:17152
	ds_read_b128 v[36:39], v157 offset:17168
	ds_read_b128 v[32:35], v157 offset:25344
	ds_read_b128 v[28:31], v157 offset:25360
	ds_read_b128 v[52:55], v157 offset:33536
	ds_read_b128 v[44:47], v157 offset:33552
	ds_read_b32 v72, v156 offset:768
	ds_read_b64 v[128:129], v155 offset:24
	s_waitcnt lgkmcnt(13)
	v_pk_mul_f32 v[160:161], v[130:131], v[160:161]
	v_pk_mul_f32 v[168:169], v[130:131], v[168:169]
	v_pk_mul_f32 v[192:193], v[192:193], v[200:201] op_sel_hi:[1,0]
	v_pk_fma_f32 v[160:161], v[132:133], v[162:163], v[160:161]
	v_pk_fma_f32 v[168:169], v[132:133], v[170:171], v[168:169]
	v_pk_mul_f32 v[194:195], v[194:195], v[200:201] op_sel_hi:[1,0]
	v_pk_fma_f32 v[160:161], v[134:135], v[164:165], v[160:161]
	v_pk_fma_f32 v[168:169], v[134:135], v[172:173], v[168:169]
	v_pk_mul_f32 v[196:197], v[196:197], v[200:201] op_sel_hi:[1,0]
	v_pk_fma_f32 v[160:161], v[136:137], v[166:167], v[160:161]
	v_pk_fma_f32 v[168:169], v[136:137], v[174:175], v[168:169]
	v_pk_mul_f32 v[198:199], v[198:199], v[200:201] op_sel_hi:[1,0]
	v_add_f32_e32 v164, v160, v161
	v_add_f32_e32 v165, v168, v169
	v_pk_fma_f32 v[192:193], v[130:131], v[176:177], v[192:193]
	v_pk_fma_f32 v[194:195], v[132:133], v[178:179], v[194:195]
	v_add_f32_dpp v164, v164, v164 quad_perm:[1,0,3,2] row_mask:0xf bank_mask:0xf bound_ctrl:1
	v_add_f32_dpp v165, v165, v165 quad_perm:[1,0,3,2] row_mask:0xf bank_mask:0xf bound_ctrl:1
	v_pk_fma_f32 v[196:197], v[134:135], v[180:181], v[196:197]
	v_add_f32_dpp v164, v164, v164 quad_perm:[2,3,0,1] row_mask:0xf bank_mask:0xf bound_ctrl:1
	v_add_f32_dpp v165, v165, v165 quad_perm:[2,3,0,1] row_mask:0xf bank_mask:0xf bound_ctrl:1
	v_pk_fma_f32 v[198:199], v[136:137], v[182:183], v[198:199]
	v_add_f32_dpp v164, v164, v164 row_half_mirror row_mask:0xf bank_mask:0xf bound_ctrl:1
	v_add_f32_dpp v165, v165, v165 row_half_mirror row_mask:0xf bank_mask:0xf bound_ctrl:1
	v_pk_fma_f32 v[130:131], v[184:185], v[164:165], v[192:193] op_sel_hi:[1,0,1]
	v_pk_fma_f32 v[132:133], v[186:187], v[164:165], v[194:195] op_sel_hi:[1,0,1]
	v_pk_fma_f32 v[134:135], v[188:189], v[164:165], v[196:197] op_sel_hi:[1,0,1]
	v_pk_fma_f32 v[136:137], v[190:191], v[164:165], v[198:199] op_sel_hi:[1,0,1]
	v_fmac_f32_e32 v165, v200, v205
	v_fmac_f32_e32 v165, v204, v164
	ds_write_b32 v158, v165 offset:384
	s_add_i32 s0, s0, 1
	v_add_u32_e32 v155, 32, v155
	v_add_u32_e32 v156, 0x400, v156
	v_add_u32_e32 v157, 0x400, v157
	s_cmp_lt_u32 s0, 8
	v_add_u32_e32 v158, 0x200, v158
	s_cbranch_scc1 .LBB0_1009
	s_mov_b64 s[0:1], 0
